# in-proj q/k epilogue: rope loads for step k+1 prefetched before step k stores; waits vmcnt(4) instead of vmcnt(0)
# speedup vs baseline: 1.0041x; 1.0041x over previous
.LBB0_832:
	v_lshlrev_b32_e32 v132, 4, v186
	s_waitcnt lgkmcnt(0)
	v_lshl_add_u64 v[128:129], s[30:31], 0, v[132:133]
	s_mov_b64 s[10:11], 0x629a000
	v_lshl_add_u64 v[162:163], v[128:129], 0, s[10:11]
	s_mov_b64 s[10:11], 0x629b000
	v_lshl_add_u64 v[164:165], v[128:129], 0, s[10:11]
	s_add_i32 s10, s17, 0xffffe000
	s_ashr_i32 s35, s17, 8
	s_andn2_b64 vcc, exec, s[8:9]
	s_ashr_i32 s38, s10, 11
	s_cbranch_vccnz .LBB0_834
	v_bfe_u32 v128, v158, 6, 5
	v_cndmask_b32_e64 v128, v217, v128, s[6:7]
	v_lshlrev_b32_e32 v132, 6, v128
	v_lshl_add_u64 v[128:129], v[164:165], 0, v[132:133]
	v_lshl_add_u64 v[160:161], v[162:163], 0, v[132:133]
	global_load_dwordx4 v[128:131], v[128:129], off
	v_and_b32_e32 v159, 0x7cf, v158
	global_load_dwordx4 v[166:169], v[160:161], off
	s_mov_b32 s10, s38
	s_waitcnt vmcnt(0)
	v_mov_b32_e32 v175, v128
	v_mov_b32_e32 v171, v130
	v_mov_b32_e32 v174, v166
	v_mov_b32_e32 v128, v167
	v_mov_b32_e32 v170, v168
	v_mov_b32_e32 v130, v169
	v_add_u32_e32 v226, 0x10, v158
	v_bfe_u32 v226, v226, 6, 5
	v_or_b32_e32 v227, 16, v217
	v_mov_b32_e32 v229, 0
	v_cndmask_b32_e64 v226, v227, v226, s[6:7]
	v_lshlrev_b32_e32 v228, 6, v226
	v_lshl_add_u64 v[222:223], v[164:165], 0, v[228:229]
	v_lshl_add_u64 v[224:225], v[162:163], 0, v[228:229]
	global_load_dwordx4 v[240:243], v[222:223], off
	global_load_dwordx4 v[244:247], v[224:225], off
	s_branch .LBB0_835

.LBB0_853:
	s_andn2_b64 vcc, exec, s[2:3]
	v_or_b32_e32 v159, 16, v217
	s_cbranch_vccnz .LBB0_859
	s_mov_b32 s2, s38
	v_and_b32_e32 v116, 0x7df, v118
	s_waitcnt vmcnt(4)
	v_mov_b32_e32 v112, v240
	v_mov_b32_e32 v113, v241
	v_mov_b32_e32 v114, v242
	v_mov_b32_e32 v115, v243
	v_mov_b32_e32 v128, v244
	v_mov_b32_e32 v129, v245
	v_mov_b32_e32 v130, v246
	v_mov_b32_e32 v131, v247
	v_mov_b32_e32 v127, v112
	v_mov_b32_e32 v125, v114
	v_mov_b32_e32 v126, v128
	v_mov_b32_e32 v112, v129
	v_mov_b32_e32 v124, v130
	v_mov_b32_e32 v114, v131
	v_add_u32_e32 v226, 0x20, v158
	v_bfe_u32 v226, v226, 6, 5
	v_or_b32_e32 v227, 32, v217
	v_mov_b32_e32 v229, 0
	v_cndmask_b32_e64 v226, v227, v226, s[6:7]
	v_lshlrev_b32_e32 v228, 6, v226
	v_lshl_add_u64 v[222:223], v[164:165], 0, v[228:229]
	v_lshl_add_u64 v[224:225], v[162:163], 0, v[228:229]
	global_load_dwordx4 v[232:235], v[222:223], off
	global_load_dwordx4 v[236:239], v[224:225], off
	s_branch .LBB0_860

.LBB0_878:
	s_andn2_b64 vcc, exec, s[2:3]
	v_or_b32_e32 v126, 32, v217
	s_cbranch_vccnz .LBB0_884
	s_mov_b32 s2, s38
	v_and_b32_e32 v100, 0x7ef, v102
	s_waitcnt vmcnt(4)
	v_mov_b32_e32 v96, v232
	v_mov_b32_e32 v97, v233
	v_mov_b32_e32 v98, v234
	v_mov_b32_e32 v99, v235
	v_mov_b32_e32 v110, v236
	v_mov_b32_e32 v111, v237
	v_mov_b32_e32 v112, v238
	v_mov_b32_e32 v113, v239
	v_mov_b32_e32 v109, v96
	v_mov_b32_e32 v107, v98
	v_mov_b32_e32 v108, v110
	v_mov_b32_e32 v96, v111
	v_mov_b32_e32 v106, v112
	v_mov_b32_e32 v98, v113
	v_add_u32_e32 v226, 0x30, v158
	v_bfe_u32 v226, v226, 6, 5
	v_or_b32_e32 v227, 48, v217
	v_mov_b32_e32 v229, 0
	v_cndmask_b32_e64 v226, v227, v226, s[6:7]
	v_lshlrev_b32_e32 v228, 6, v226
	v_lshl_add_u64 v[222:223], v[164:165], 0, v[228:229]
	v_lshl_add_u64 v[224:225], v[162:163], 0, v[228:229]
	global_load_dwordx4 v[240:243], v[222:223], off
	global_load_dwordx4 v[244:247], v[224:225], off
	s_branch .LBB0_885

.LBB0_903:
	s_andn2_b64 vcc, exec, s[2:3]
	v_or_b32_e32 v108, 48, v217
	s_cbranch_vccnz .LBB0_909
	s_mov_b32 s35, s38
	v_and_b32_e32 v84, 0x7ff, v86
	s_waitcnt vmcnt(4)
	v_mov_b32_e32 v80, v240
	v_mov_b32_e32 v81, v241
	v_mov_b32_e32 v82, v242
	v_mov_b32_e32 v83, v243
	v_mov_b32_e32 v94, v244
	v_mov_b32_e32 v95, v245
	v_mov_b32_e32 v96, v246
	v_mov_b32_e32 v97, v247
	v_mov_b32_e32 v93, v80
	v_mov_b32_e32 v91, v82
	v_mov_b32_e32 v92, v94
	v_mov_b32_e32 v80, v95
	v_mov_b32_e32 v90, v96
	v_mov_b32_e32 v82, v97
	v_add_u32_e32 v226, 0x80, v158
	v_bfe_u32 v226, v226, 6, 5
	v_or_b32_e32 v227, 0, v217
	v_mov_b32_e32 v229, 0
	v_cndmask_b32_e64 v226, v227, v226, s[6:7]
	v_lshlrev_b32_e32 v228, 6, v226
	v_lshl_add_u64 v[222:223], v[164:165], 0, v[228:229]
	v_lshl_add_u64 v[224:225], v[162:163], 0, v[228:229]
	global_load_dwordx4 v[232:235], v[222:223], off
	global_load_dwordx4 v[236:239], v[224:225], off
	s_branch .LBB0_910

.LBB0_928:
	s_addk_i32 s17, 0xe080
	v_ashrrev_i32_e32 v94, 8, v70
	s_andn2_b64 vcc, exec, s[2:3]
	s_ashr_i32 s17, s17, 11
	s_cbranch_vccnz .LBB0_934
	v_and_b32_e32 v68, 0x7cf, v70
	v_mov_b32_e32 v69, s17
	s_waitcnt vmcnt(4)
	v_mov_b32_e32 v64, v232
	v_mov_b32_e32 v65, v233
	v_mov_b32_e32 v66, v234
	v_mov_b32_e32 v67, v235
	v_mov_b32_e32 v78, v236
	v_mov_b32_e32 v79, v237
	v_mov_b32_e32 v80, v238
	v_mov_b32_e32 v81, v239
	v_mov_b32_e32 v77, v64
	v_mov_b32_e32 v75, v66
	v_mov_b32_e32 v76, v78
	v_mov_b32_e32 v64, v79
	v_mov_b32_e32 v74, v80
	v_mov_b32_e32 v66, v81
	v_add_u32_e32 v226, 0x90, v158
	v_bfe_u32 v226, v226, 6, 5
	v_or_b32_e32 v227, 16, v217
	v_mov_b32_e32 v229, 0
	v_cndmask_b32_e64 v226, v227, v226, s[6:7]
	v_lshlrev_b32_e32 v228, 6, v226
	v_lshl_add_u64 v[222:223], v[164:165], 0, v[228:229]
	v_lshl_add_u64 v[224:225], v[162:163], 0, v[228:229]
	global_load_dwordx4 v[240:243], v[222:223], off
	global_load_dwordx4 v[244:247], v[224:225], off
	s_branch .LBB0_935

.LBB0_953:
	s_andn2_b64 vcc, exec, s[2:3]
	s_cbranch_vccnz .LBB0_959
	v_and_b32_e32 v52, 0x7df, v54
	v_mov_b32_e32 v53, s17
	s_waitcnt vmcnt(4)
	v_mov_b32_e32 v48, v240
	v_mov_b32_e32 v49, v241
	v_mov_b32_e32 v50, v242
	v_mov_b32_e32 v51, v243
	v_mov_b32_e32 v62, v244
	v_mov_b32_e32 v63, v245
	v_mov_b32_e32 v64, v246
	v_mov_b32_e32 v65, v247
	v_mov_b32_e32 v61, v48
	v_mov_b32_e32 v59, v50
	v_mov_b32_e32 v60, v62
	v_mov_b32_e32 v48, v63
	v_mov_b32_e32 v58, v64
	v_mov_b32_e32 v50, v65
	v_add_u32_e32 v226, 0xa0, v158
	v_bfe_u32 v226, v226, 6, 5
	v_or_b32_e32 v227, 32, v217
	v_mov_b32_e32 v229, 0
	v_cndmask_b32_e64 v226, v227, v226, s[6:7]
	v_lshlrev_b32_e32 v228, 6, v226
	v_lshl_add_u64 v[222:223], v[164:165], 0, v[228:229]
	v_lshl_add_u64 v[224:225], v[162:163], 0, v[228:229]
	global_load_dwordx4 v[232:235], v[222:223], off
	global_load_dwordx4 v[236:239], v[224:225], off
	s_branch .LBB0_960

.LBB0_978:
	s_andn2_b64 vcc, exec, s[2:3]
	s_cbranch_vccnz .LBB0_984
	v_and_b32_e32 v36, 0x7ef, v38
	v_mov_b32_e32 v37, s17
	s_waitcnt vmcnt(4)
	v_mov_b32_e32 v32, v232
	v_mov_b32_e32 v33, v233
	v_mov_b32_e32 v34, v234
	v_mov_b32_e32 v35, v235
	v_mov_b32_e32 v46, v236
	v_mov_b32_e32 v47, v237
	v_mov_b32_e32 v48, v238
	v_mov_b32_e32 v49, v239
	v_mov_b32_e32 v45, v32
	v_mov_b32_e32 v43, v34
	v_mov_b32_e32 v44, v46
	v_mov_b32_e32 v32, v47
	v_mov_b32_e32 v42, v48
	v_mov_b32_e32 v34, v49
	v_add_u32_e32 v226, 0xb0, v158
	v_bfe_u32 v226, v226, 6, 5
	v_or_b32_e32 v227, 48, v217
	v_mov_b32_e32 v229, 0
	v_cndmask_b32_e64 v226, v227, v226, s[6:7]
	v_lshlrev_b32_e32 v228, 6, v226
	v_lshl_add_u64 v[222:223], v[164:165], 0, v[228:229]
	v_lshl_add_u64 v[224:225], v[162:163], 0, v[228:229]
	global_load_dwordx4 v[240:243], v[222:223], off
	global_load_dwordx4 v[244:247], v[224:225], off
	s_branch .LBB0_985

.LBB0_1003:
	s_andn2_b64 vcc, exec, s[2:3]
	s_cbranch_vccnz .LBB0_1009
	v_mov_b32_e32 v94, s17
	v_and_b32_e32 v20, 0x7ff, v22
	s_waitcnt vmcnt(4)
	v_mov_b32_e32 v16, v240
	v_mov_b32_e32 v17, v241
	v_mov_b32_e32 v18, v242
	v_mov_b32_e32 v19, v243
	v_mov_b32_e32 v30, v244
	v_mov_b32_e32 v31, v245
	v_mov_b32_e32 v32, v246
	v_mov_b32_e32 v33, v247
	v_mov_b32_e32 v29, v16
	v_mov_b32_e32 v27, v18
	v_mov_b32_e32 v28, v30
	v_mov_b32_e32 v16, v31
	v_mov_b32_e32 v26, v32
	v_mov_b32_e32 v18, v33
	s_branch .LBB0_1010
